# BM selected-attention tail split in halves: exp/sum/cvt of key tiles 0-1, PV k-step 0 MFMAs, then exp/sum/cvt of tiles 2-3 under those MFMAs, PV k-step 1
# speedup vs baseline: 1.0019x; 1.0019x over previous
.Lbm2_Ag0_exp:
	v_exp_f32_e32 v84, v84
	v_exp_f32_e32 v85, v85
	v_exp_f32_e32 v86, v86
	v_exp_f32_e32 v87, v87
	v_exp_f32_e32 v88, v88
	v_exp_f32_e32 v89, v89
	v_exp_f32_e32 v90, v90
	v_exp_f32_e32 v91, v91
	s_nop 0
	v_pk_add_f32 v[248:249], v[84:85], v[86:87]
	v_pk_add_f32 v[248:249], v[248:249], v[88:89]
	v_pk_add_f32 v[248:249], v[248:249], v[90:91]
	v_cvt_pk_fp8_f32 v84, v84, v85
	v_cvt_pk_fp8_f32 v85, v88, v89
	v_cvt_pk_fp8_f32 v84, v86, v87 op_sel:[0,0,1]
	v_cvt_pk_fp8_f32 v85, v90, v91 op_sel:[0,0,1]
	s_waitcnt vmcnt(8)
	s_nop 1
	v_mfma_f32_16x16x32_fp8_fp8 v[100:103], v[36:37], v[84:85], v[100:103]
	v_mfma_f32_16x16x32_fp8_fp8 v[104:107], v[38:39], v[84:85], v[104:107]
	v_mfma_f32_16x16x32_fp8_fp8 v[108:111], v[40:41], v[84:85], v[108:111]
	v_mfma_f32_16x16x32_fp8_fp8 v[112:115], v[42:43], v[84:85], v[112:115]
	v_exp_f32_e32 v92, v92
	v_exp_f32_e32 v93, v93
	v_exp_f32_e32 v94, v94
	v_exp_f32_e32 v95, v95
	v_exp_f32_e32 v96, v96
	v_exp_f32_e32 v97, v97
	v_exp_f32_e32 v98, v98
	v_exp_f32_e32 v99, v99
	s_nop 0
	v_pk_add_f32 v[248:249], v[248:249], v[92:93]
	v_pk_add_f32 v[248:249], v[248:249], v[94:95]
	v_pk_add_f32 v[248:249], v[248:249], v[96:97]
	v_pk_add_f32 v[248:249], v[248:249], v[98:99]
	v_add_f32_e32 v248, v248, v249
	v_add_f32_e32 v194, v194, v248
	v_cvt_pk_fp8_f32 v86, v92, v93
	v_cvt_pk_fp8_f32 v87, v96, v97
	v_cvt_pk_fp8_f32 v86, v94, v95 op_sel:[0,0,1]
	v_cvt_pk_fp8_f32 v87, v98, v99 op_sel:[0,0,1]
	s_nop 1
	v_mfma_f32_16x16x32_fp8_fp8 v[100:103], v[44:45], v[86:87], v[100:103]
	v_mfma_f32_16x16x32_fp8_fp8 v[104:107], v[46:47], v[86:87], v[104:107]
	v_mfma_f32_16x16x32_fp8_fp8 v[108:111], v[48:49], v[86:87], v[108:111]
	v_mfma_f32_16x16x32_fp8_fp8 v[112:115], v[50:51], v[86:87], v[112:115]
	s_branch .Lbm2_Ag0_skip

.Lbm2_Ag1_exp:
	v_exp_f32_e32 v84, v84
	v_exp_f32_e32 v85, v85
	v_exp_f32_e32 v86, v86
	v_exp_f32_e32 v87, v87
	v_exp_f32_e32 v88, v88
	v_exp_f32_e32 v89, v89
	v_exp_f32_e32 v90, v90
	v_exp_f32_e32 v91, v91
	s_nop 0
	v_pk_add_f32 v[248:249], v[84:85], v[86:87]
	v_pk_add_f32 v[248:249], v[248:249], v[88:89]
	v_pk_add_f32 v[248:249], v[248:249], v[90:91]
	v_cvt_pk_fp8_f32 v84, v84, v85
	v_cvt_pk_fp8_f32 v85, v88, v89
	v_cvt_pk_fp8_f32 v84, v86, v87 op_sel:[0,0,1]
	v_cvt_pk_fp8_f32 v85, v90, v91 op_sel:[0,0,1]
	s_waitcnt vmcnt(8)
	s_nop 1
	v_mfma_f32_16x16x32_fp8_fp8 v[116:119], v[36:37], v[84:85], v[116:119]
	v_mfma_f32_16x16x32_fp8_fp8 v[120:123], v[38:39], v[84:85], v[120:123]
	v_mfma_f32_16x16x32_fp8_fp8 v[124:127], v[40:41], v[84:85], v[124:127]
	v_mfma_f32_16x16x32_fp8_fp8 v[128:131], v[42:43], v[84:85], v[128:131]
	v_exp_f32_e32 v92, v92
	v_exp_f32_e32 v93, v93
	v_exp_f32_e32 v94, v94
	v_exp_f32_e32 v95, v95
	v_exp_f32_e32 v96, v96
	v_exp_f32_e32 v97, v97
	v_exp_f32_e32 v98, v98
	v_exp_f32_e32 v99, v99
	s_nop 0
	v_pk_add_f32 v[248:249], v[248:249], v[92:93]
	v_pk_add_f32 v[248:249], v[248:249], v[94:95]
	v_pk_add_f32 v[248:249], v[248:249], v[96:97]
	v_pk_add_f32 v[248:249], v[248:249], v[98:99]
	v_add_f32_e32 v248, v248, v249
	v_add_f32_e32 v195, v195, v248
	v_cvt_pk_fp8_f32 v86, v92, v93
	v_cvt_pk_fp8_f32 v87, v96, v97
	v_cvt_pk_fp8_f32 v86, v94, v95 op_sel:[0,0,1]
	v_cvt_pk_fp8_f32 v87, v98, v99 op_sel:[0,0,1]
	s_nop 1
	v_mfma_f32_16x16x32_fp8_fp8 v[116:119], v[44:45], v[86:87], v[116:119]
	v_mfma_f32_16x16x32_fp8_fp8 v[120:123], v[46:47], v[86:87], v[120:123]
	v_mfma_f32_16x16x32_fp8_fp8 v[124:127], v[48:49], v[86:87], v[124:127]
	v_mfma_f32_16x16x32_fp8_fp8 v[128:131], v[50:51], v[86:87], v[128:131]
	s_branch .Lbm2_Ag1_skip

.Lbm2_Ag2_exp:
	v_exp_f32_e32 v84, v84
	v_exp_f32_e32 v85, v85
	v_exp_f32_e32 v86, v86
	v_exp_f32_e32 v87, v87
	v_exp_f32_e32 v88, v88
	v_exp_f32_e32 v89, v89
	v_exp_f32_e32 v90, v90
	v_exp_f32_e32 v91, v91
	s_nop 0
	v_pk_add_f32 v[248:249], v[84:85], v[86:87]
	v_pk_add_f32 v[248:249], v[248:249], v[88:89]
	v_pk_add_f32 v[248:249], v[248:249], v[90:91]
	v_cvt_pk_fp8_f32 v84, v84, v85
	v_cvt_pk_fp8_f32 v85, v88, v89
	v_cvt_pk_fp8_f32 v84, v86, v87 op_sel:[0,0,1]
	v_cvt_pk_fp8_f32 v85, v90, v91 op_sel:[0,0,1]
	s_waitcnt vmcnt(8)
	s_nop 1
	v_mfma_f32_16x16x32_fp8_fp8 v[132:135], v[36:37], v[84:85], v[132:135]
	v_mfma_f32_16x16x32_fp8_fp8 v[136:139], v[38:39], v[84:85], v[136:139]
	v_mfma_f32_16x16x32_fp8_fp8 v[140:143], v[40:41], v[84:85], v[140:143]
	v_mfma_f32_16x16x32_fp8_fp8 v[144:147], v[42:43], v[84:85], v[144:147]
	v_exp_f32_e32 v92, v92
	v_exp_f32_e32 v93, v93
	v_exp_f32_e32 v94, v94
	v_exp_f32_e32 v95, v95
	v_exp_f32_e32 v96, v96
	v_exp_f32_e32 v97, v97
	v_exp_f32_e32 v98, v98
	v_exp_f32_e32 v99, v99
	s_nop 0
	v_pk_add_f32 v[248:249], v[248:249], v[92:93]
	v_pk_add_f32 v[248:249], v[248:249], v[94:95]
	v_pk_add_f32 v[248:249], v[248:249], v[96:97]
	v_pk_add_f32 v[248:249], v[248:249], v[98:99]
	v_add_f32_e32 v248, v248, v249
	v_add_f32_e32 v196, v196, v248
	v_cvt_pk_fp8_f32 v86, v92, v93
	v_cvt_pk_fp8_f32 v87, v96, v97
	v_cvt_pk_fp8_f32 v86, v94, v95 op_sel:[0,0,1]
	v_cvt_pk_fp8_f32 v87, v98, v99 op_sel:[0,0,1]
	s_nop 1
	v_mfma_f32_16x16x32_fp8_fp8 v[132:135], v[44:45], v[86:87], v[132:135]
	v_mfma_f32_16x16x32_fp8_fp8 v[136:139], v[46:47], v[86:87], v[136:139]
	v_mfma_f32_16x16x32_fp8_fp8 v[140:143], v[48:49], v[86:87], v[140:143]
	v_mfma_f32_16x16x32_fp8_fp8 v[144:147], v[50:51], v[86:87], v[144:147]
	s_branch .Lbm2_Ag2_skip

.Lbm2_Ag3_exp:
	v_exp_f32_e32 v84, v84
	v_exp_f32_e32 v85, v85
	v_exp_f32_e32 v86, v86
	v_exp_f32_e32 v87, v87
	v_exp_f32_e32 v88, v88
	v_exp_f32_e32 v89, v89
	v_exp_f32_e32 v90, v90
	v_exp_f32_e32 v91, v91
	s_nop 0
	v_pk_add_f32 v[248:249], v[84:85], v[86:87]
	v_pk_add_f32 v[248:249], v[248:249], v[88:89]
	v_pk_add_f32 v[248:249], v[248:249], v[90:91]
	v_cvt_pk_fp8_f32 v84, v84, v85
	v_cvt_pk_fp8_f32 v85, v88, v89
	v_cvt_pk_fp8_f32 v84, v86, v87 op_sel:[0,0,1]
	v_cvt_pk_fp8_f32 v85, v90, v91 op_sel:[0,0,1]
	s_waitcnt vmcnt(8)
	s_nop 1
	v_mfma_f32_16x16x32_fp8_fp8 v[148:151], v[36:37], v[84:85], v[148:151]
	v_mfma_f32_16x16x32_fp8_fp8 v[152:155], v[38:39], v[84:85], v[152:155]
	v_mfma_f32_16x16x32_fp8_fp8 v[156:159], v[40:41], v[84:85], v[156:159]
	v_mfma_f32_16x16x32_fp8_fp8 v[160:163], v[42:43], v[84:85], v[160:163]
	v_exp_f32_e32 v92, v92
	v_exp_f32_e32 v93, v93
	v_exp_f32_e32 v94, v94
	v_exp_f32_e32 v95, v95
	v_exp_f32_e32 v96, v96
	v_exp_f32_e32 v97, v97
	v_exp_f32_e32 v98, v98
	v_exp_f32_e32 v99, v99
	s_nop 0
	v_pk_add_f32 v[248:249], v[248:249], v[92:93]
	v_pk_add_f32 v[248:249], v[248:249], v[94:95]
	v_pk_add_f32 v[248:249], v[248:249], v[96:97]
	v_pk_add_f32 v[248:249], v[248:249], v[98:99]
	v_add_f32_e32 v248, v248, v249
	v_add_f32_e32 v197, v197, v248
	v_cvt_pk_fp8_f32 v86, v92, v93
	v_cvt_pk_fp8_f32 v87, v96, v97
	v_cvt_pk_fp8_f32 v86, v94, v95 op_sel:[0,0,1]
	v_cvt_pk_fp8_f32 v87, v98, v99 op_sel:[0,0,1]
	s_nop 1
	v_mfma_f32_16x16x32_fp8_fp8 v[148:151], v[44:45], v[86:87], v[148:151]
	v_mfma_f32_16x16x32_fp8_fp8 v[152:155], v[46:47], v[86:87], v[152:155]
	v_mfma_f32_16x16x32_fp8_fp8 v[156:159], v[48:49], v[86:87], v[156:159]
	v_mfma_f32_16x16x32_fp8_fp8 v[160:163], v[50:51], v[86:87], v[160:163]
	s_branch .Lbm2_Ag3_skip

.Lbm2_Bg0_exp:
	v_exp_f32_e32 v84, v84
	v_exp_f32_e32 v85, v85
	v_exp_f32_e32 v86, v86
	v_exp_f32_e32 v87, v87
	v_exp_f32_e32 v88, v88
	v_exp_f32_e32 v89, v89
	v_exp_f32_e32 v90, v90
	v_exp_f32_e32 v91, v91
	s_nop 0
	v_pk_add_f32 v[248:249], v[84:85], v[86:87]
	v_pk_add_f32 v[248:249], v[248:249], v[88:89]
	v_pk_add_f32 v[248:249], v[248:249], v[90:91]
	v_cvt_pk_fp8_f32 v84, v84, v85
	v_cvt_pk_fp8_f32 v85, v88, v89
	v_cvt_pk_fp8_f32 v84, v86, v87 op_sel:[0,0,1]
	v_cvt_pk_fp8_f32 v85, v90, v91 op_sel:[0,0,1]
	s_waitcnt vmcnt(8)
	s_nop 1
	v_mfma_f32_16x16x32_fp8_fp8 v[100:103], v[52:53], v[84:85], v[100:103]
	v_mfma_f32_16x16x32_fp8_fp8 v[104:107], v[54:55], v[84:85], v[104:107]
	v_mfma_f32_16x16x32_fp8_fp8 v[108:111], v[56:57], v[84:85], v[108:111]
	v_mfma_f32_16x16x32_fp8_fp8 v[112:115], v[58:59], v[84:85], v[112:115]
	v_exp_f32_e32 v92, v92
	v_exp_f32_e32 v93, v93
	v_exp_f32_e32 v94, v94
	v_exp_f32_e32 v95, v95
	v_exp_f32_e32 v96, v96
	v_exp_f32_e32 v97, v97
	v_exp_f32_e32 v98, v98
	v_exp_f32_e32 v99, v99
	s_nop 0
	v_pk_add_f32 v[248:249], v[248:249], v[92:93]
	v_pk_add_f32 v[248:249], v[248:249], v[94:95]
	v_pk_add_f32 v[248:249], v[248:249], v[96:97]
	v_pk_add_f32 v[248:249], v[248:249], v[98:99]
	v_add_f32_e32 v248, v248, v249
	v_add_f32_e32 v194, v194, v248
	v_cvt_pk_fp8_f32 v86, v92, v93
	v_cvt_pk_fp8_f32 v87, v96, v97
	v_cvt_pk_fp8_f32 v86, v94, v95 op_sel:[0,0,1]
	v_cvt_pk_fp8_f32 v87, v98, v99 op_sel:[0,0,1]
	s_nop 1
	v_mfma_f32_16x16x32_fp8_fp8 v[100:103], v[60:61], v[86:87], v[100:103]
	v_mfma_f32_16x16x32_fp8_fp8 v[104:107], v[62:63], v[86:87], v[104:107]
	v_mfma_f32_16x16x32_fp8_fp8 v[108:111], v[64:65], v[86:87], v[108:111]
	v_mfma_f32_16x16x32_fp8_fp8 v[112:115], v[66:67], v[86:87], v[112:115]
	s_branch .Lbm2_Bg0_skip

.Lbm2_Bg1_exp:
	v_exp_f32_e32 v84, v84
	v_exp_f32_e32 v85, v85
	v_exp_f32_e32 v86, v86
	v_exp_f32_e32 v87, v87
	v_exp_f32_e32 v88, v88
	v_exp_f32_e32 v89, v89
	v_exp_f32_e32 v90, v90
	v_exp_f32_e32 v91, v91
	s_nop 0
	v_pk_add_f32 v[248:249], v[84:85], v[86:87]
	v_pk_add_f32 v[248:249], v[248:249], v[88:89]
	v_pk_add_f32 v[248:249], v[248:249], v[90:91]
	v_cvt_pk_fp8_f32 v84, v84, v85
	v_cvt_pk_fp8_f32 v85, v88, v89
	v_cvt_pk_fp8_f32 v84, v86, v87 op_sel:[0,0,1]
	v_cvt_pk_fp8_f32 v85, v90, v91 op_sel:[0,0,1]
	s_waitcnt vmcnt(8)
	s_nop 1
	v_mfma_f32_16x16x32_fp8_fp8 v[116:119], v[52:53], v[84:85], v[116:119]
	v_mfma_f32_16x16x32_fp8_fp8 v[120:123], v[54:55], v[84:85], v[120:123]
	v_mfma_f32_16x16x32_fp8_fp8 v[124:127], v[56:57], v[84:85], v[124:127]
	v_mfma_f32_16x16x32_fp8_fp8 v[128:131], v[58:59], v[84:85], v[128:131]
	v_exp_f32_e32 v92, v92
	v_exp_f32_e32 v93, v93
	v_exp_f32_e32 v94, v94
	v_exp_f32_e32 v95, v95
	v_exp_f32_e32 v96, v96
	v_exp_f32_e32 v97, v97
	v_exp_f32_e32 v98, v98
	v_exp_f32_e32 v99, v99
	s_nop 0
	v_pk_add_f32 v[248:249], v[248:249], v[92:93]
	v_pk_add_f32 v[248:249], v[248:249], v[94:95]
	v_pk_add_f32 v[248:249], v[248:249], v[96:97]
	v_pk_add_f32 v[248:249], v[248:249], v[98:99]
	v_add_f32_e32 v248, v248, v249
	v_add_f32_e32 v195, v195, v248
	v_cvt_pk_fp8_f32 v86, v92, v93
	v_cvt_pk_fp8_f32 v87, v96, v97
	v_cvt_pk_fp8_f32 v86, v94, v95 op_sel:[0,0,1]
	v_cvt_pk_fp8_f32 v87, v98, v99 op_sel:[0,0,1]
	s_nop 1
	v_mfma_f32_16x16x32_fp8_fp8 v[116:119], v[60:61], v[86:87], v[116:119]
	v_mfma_f32_16x16x32_fp8_fp8 v[120:123], v[62:63], v[86:87], v[120:123]
	v_mfma_f32_16x16x32_fp8_fp8 v[124:127], v[64:65], v[86:87], v[124:127]
	v_mfma_f32_16x16x32_fp8_fp8 v[128:131], v[66:67], v[86:87], v[128:131]
	s_branch .Lbm2_Bg1_skip

.Lbm2_Bg2_exp:
	v_exp_f32_e32 v84, v84
	v_exp_f32_e32 v85, v85
	v_exp_f32_e32 v86, v86
	v_exp_f32_e32 v87, v87
	v_exp_f32_e32 v88, v88
	v_exp_f32_e32 v89, v89
	v_exp_f32_e32 v90, v90
	v_exp_f32_e32 v91, v91
	s_nop 0
	v_pk_add_f32 v[248:249], v[84:85], v[86:87]
	v_pk_add_f32 v[248:249], v[248:249], v[88:89]
	v_pk_add_f32 v[248:249], v[248:249], v[90:91]
	v_cvt_pk_fp8_f32 v84, v84, v85
	v_cvt_pk_fp8_f32 v85, v88, v89
	v_cvt_pk_fp8_f32 v84, v86, v87 op_sel:[0,0,1]
	v_cvt_pk_fp8_f32 v85, v90, v91 op_sel:[0,0,1]
	s_waitcnt vmcnt(8)
	s_nop 1
	v_mfma_f32_16x16x32_fp8_fp8 v[132:135], v[52:53], v[84:85], v[132:135]
	v_mfma_f32_16x16x32_fp8_fp8 v[136:139], v[54:55], v[84:85], v[136:139]
	v_mfma_f32_16x16x32_fp8_fp8 v[140:143], v[56:57], v[84:85], v[140:143]
	v_mfma_f32_16x16x32_fp8_fp8 v[144:147], v[58:59], v[84:85], v[144:147]
	v_exp_f32_e32 v92, v92
	v_exp_f32_e32 v93, v93
	v_exp_f32_e32 v94, v94
	v_exp_f32_e32 v95, v95
	v_exp_f32_e32 v96, v96
	v_exp_f32_e32 v97, v97
	v_exp_f32_e32 v98, v98
	v_exp_f32_e32 v99, v99
	s_nop 0
	v_pk_add_f32 v[248:249], v[248:249], v[92:93]
	v_pk_add_f32 v[248:249], v[248:249], v[94:95]
	v_pk_add_f32 v[248:249], v[248:249], v[96:97]
	v_pk_add_f32 v[248:249], v[248:249], v[98:99]
	v_add_f32_e32 v248, v248, v249
	v_add_f32_e32 v196, v196, v248
	v_cvt_pk_fp8_f32 v86, v92, v93
	v_cvt_pk_fp8_f32 v87, v96, v97
	v_cvt_pk_fp8_f32 v86, v94, v95 op_sel:[0,0,1]
	v_cvt_pk_fp8_f32 v87, v98, v99 op_sel:[0,0,1]
	s_nop 1
	v_mfma_f32_16x16x32_fp8_fp8 v[132:135], v[60:61], v[86:87], v[132:135]
	v_mfma_f32_16x16x32_fp8_fp8 v[136:139], v[62:63], v[86:87], v[136:139]
	v_mfma_f32_16x16x32_fp8_fp8 v[140:143], v[64:65], v[86:87], v[140:143]
	v_mfma_f32_16x16x32_fp8_fp8 v[144:147], v[66:67], v[86:87], v[144:147]
	s_branch .Lbm2_Bg2_skip

.Lbm2_Bg3_exp:
	v_exp_f32_e32 v84, v84
	v_exp_f32_e32 v85, v85
	v_exp_f32_e32 v86, v86
	v_exp_f32_e32 v87, v87
	v_exp_f32_e32 v88, v88
	v_exp_f32_e32 v89, v89
	v_exp_f32_e32 v90, v90
	v_exp_f32_e32 v91, v91
	s_nop 0
	v_pk_add_f32 v[248:249], v[84:85], v[86:87]
	v_pk_add_f32 v[248:249], v[248:249], v[88:89]
	v_pk_add_f32 v[248:249], v[248:249], v[90:91]
	v_cvt_pk_fp8_f32 v84, v84, v85
	v_cvt_pk_fp8_f32 v85, v88, v89
	v_cvt_pk_fp8_f32 v84, v86, v87 op_sel:[0,0,1]
	v_cvt_pk_fp8_f32 v85, v90, v91 op_sel:[0,0,1]
	s_waitcnt vmcnt(8)
	s_nop 1
	v_mfma_f32_16x16x32_fp8_fp8 v[148:151], v[52:53], v[84:85], v[148:151]
	v_mfma_f32_16x16x32_fp8_fp8 v[152:155], v[54:55], v[84:85], v[152:155]
	v_mfma_f32_16x16x32_fp8_fp8 v[156:159], v[56:57], v[84:85], v[156:159]
	v_mfma_f32_16x16x32_fp8_fp8 v[160:163], v[58:59], v[84:85], v[160:163]
	v_exp_f32_e32 v92, v92
	v_exp_f32_e32 v93, v93
	v_exp_f32_e32 v94, v94
	v_exp_f32_e32 v95, v95
	v_exp_f32_e32 v96, v96
	v_exp_f32_e32 v97, v97
	v_exp_f32_e32 v98, v98
	v_exp_f32_e32 v99, v99
	s_nop 0
	v_pk_add_f32 v[248:249], v[248:249], v[92:93]
	v_pk_add_f32 v[248:249], v[248:249], v[94:95]
	v_pk_add_f32 v[248:249], v[248:249], v[96:97]
	v_pk_add_f32 v[248:249], v[248:249], v[98:99]
	v_add_f32_e32 v248, v248, v249
	v_add_f32_e32 v197, v197, v248
	v_cvt_pk_fp8_f32 v86, v92, v93
	v_cvt_pk_fp8_f32 v87, v96, v97
	v_cvt_pk_fp8_f32 v86, v94, v95 op_sel:[0,0,1]
	v_cvt_pk_fp8_f32 v87, v98, v99 op_sel:[0,0,1]
	s_nop 1
	v_mfma_f32_16x16x32_fp8_fp8 v[148:151], v[60:61], v[86:87], v[148:151]
	v_mfma_f32_16x16x32_fp8_fp8 v[152:155], v[62:63], v[86:87], v[152:155]
	v_mfma_f32_16x16x32_fp8_fp8 v[156:159], v[64:65], v[86:87], v[156:159]
	v_mfma_f32_16x16x32_fp8_fp8 v[160:163], v[66:67], v[86:87], v[160:163]
	s_branch .Lbm2_Bg3_skip
